# r45 + gdn_pre causal-conv+SiLU loop unrolled x6 and software-pipelined (next item's 8 LDS reads issued before the SiLU tail)
# baseline (speedup 1.0000x reference)
.LBB0_314:
	v_mul_hi_i32 v5, v4, s61
	v_lshrrev_b32_e32 v10, 31, v5
	v_ashrrev_i32_e32 v5, 3, v5
	v_and_b32_e32 v8, 60, v3
	v_add_u32_e32 v3, 0x800, v3
	v_add_u32_e32 v5, v5, v10
	s_movk_i32 s44, 0xffd0
	v_add_u32_e32 v9, 0x200, v4
	v_mad_u64_u32 v[16:17], s[44:45], v5, s44, v[4:5]
	v_mad_u64_u32 v[152:153], s[44:45], v5, s40, v[2:3]
	v_lshlrev_b32_e32 v59, 2, v8
	v_lshl_add_u32 v17, v5, 4, v2
	v_mov_b32_e32 v4, v9
	ds_read_b128 v[8:11], v152
	ds_read_b128 v[12:15], v152 offset:768
	v_add_u32_e32 v156, 0xfffeabd0, v17
	v_cmp_gt_u32_e32 vcc, 32, v16
	v_mov_b32_e32 v157, 0x210
	v_mov_b32_e32 v158, 0x110
	v_add_u32_e32 v160, 0xfffeaee0, v17
	v_add_u32_e32 v161, 0xfffeb1f0, v17
	ds_read_b128 v[148:151], v152 offset:1536
	ds_read_b128 v[152:155], v152 offset:2304
	v_add_u32_e32 v17, 0xfffeb500, v17
	v_cndmask_b32_e32 v179, v157, v158, vcc
	ds_read_b128 v[156:159], v156
	ds_read_b128 v[166:169], v160
	ds_read_b128 v[170:173], v161
	ds_read_b128 v[174:177], v17
	v_and_b32_e32 v178, -16, v16
	s_waitcnt lgkmcnt(3)
	v_pk_fma_f32 v[200:201], v[10:11], v[158:159], 0 op_sel_hi:[1,1,0]
	v_pk_fma_f32 v[198:199], v[8:9], v[156:157], 0 op_sel_hi:[1,1,0]
	s_waitcnt lgkmcnt(2)
	v_pk_fma_f32 v[200:201], v[14:15], v[168:169], v[200:201]
	v_pk_fma_f32 v[198:199], v[12:13], v[166:167], v[198:199]
	s_waitcnt lgkmcnt(1)
	v_pk_fma_f32 v[200:201], v[150:151], v[172:173], v[200:201]
	v_pk_fma_f32 v[198:199], v[148:149], v[170:171], v[198:199]
	s_waitcnt lgkmcnt(0)
	v_pk_fma_f32 v[200:201], v[154:155], v[176:177], v[200:201]
	v_pk_fma_f32 v[198:199], v[152:153], v[174:175], v[198:199]
	v_mov_b32_e32 v208, v16
	v_mov_b32_e32 v209, v5
	v_mov_b32_e32 v210, v179
	v_mov_b32_e32 v211, v59
	v_mov_b32_e32 v212, v178
	v_add_u32_e32 v2, 0x2000, v2
	v_mul_hi_i32 v5, v4, s61
	v_lshrrev_b32_e32 v10, 31, v5
	v_ashrrev_i32_e32 v5, 3, v5
	v_and_b32_e32 v8, 60, v3
	v_add_u32_e32 v3, 0x800, v3
	v_add_u32_e32 v5, v5, v10
	s_movk_i32 s44, 0xffd0
	v_add_u32_e32 v9, 0x200, v4
	v_mad_u64_u32 v[16:17], s[44:45], v5, s44, v[4:5]
	v_mad_u64_u32 v[152:153], s[44:45], v5, s40, v[2:3]
	v_lshlrev_b32_e32 v59, 2, v8
	v_lshl_add_u32 v17, v5, 4, v2
	v_mov_b32_e32 v4, v9
	ds_read_b128 v[8:11], v152
	ds_read_b128 v[12:15], v152 offset:768
	v_add_u32_e32 v156, 0xfffeabd0, v17
	v_cmp_gt_u32_e32 vcc, 32, v16
	v_mov_b32_e32 v157, 0x210
	v_mov_b32_e32 v158, 0x110
	v_add_u32_e32 v160, 0xfffeaee0, v17
	v_add_u32_e32 v161, 0xfffeb1f0, v17
	ds_read_b128 v[148:151], v152 offset:1536
	ds_read_b128 v[152:155], v152 offset:2304
	v_add_u32_e32 v17, 0xfffeb500, v17
	v_cndmask_b32_e32 v179, v157, v158, vcc
	ds_read_b128 v[156:159], v156
	ds_read_b128 v[166:169], v160
	ds_read_b128 v[170:173], v161
	ds_read_b128 v[174:177], v17
	v_and_b32_e32 v178, -16, v16
	v_mul_f32_e32 v204, 0xbfb8aa3b, v200
	v_mul_f32_e32 v202, 0xbfb8aa3b, v198
	v_mul_f32_e32 v203, 0xbfb8aa3b, v199
	v_mul_f32_e32 v205, 0xbfb8aa3b, v201
	v_exp_f32_e32 v202, v202
	v_exp_f32_e32 v203, v203
	v_exp_f32_e32 v204, v204
	v_exp_f32_e32 v205, v205
	v_add_f32_e32 v202, 1.0, v202
	v_add_f32_e32 v203, 1.0, v203
	v_add_f32_e32 v204, 1.0, v204
	v_add_f32_e32 v205, 1.0, v205
	v_cmp_eq_u32_e32 vcc, 16, v212
	v_mov_b32_e32 v206, 0x15530
	v_mov_b32_e32 v207, 0x4400
	v_rcp_f32_e32 v202, v202
	v_rcp_f32_e32 v204, v204
	v_rcp_f32_e32 v205, v205
	v_rcp_f32_e32 v203, v203
	v_cndmask_b32_e32 v206, v206, v207, vcc
	v_add_u32_e32 v206, 0, v206
	v_cmp_gt_u32_e32 vcc, 16, v208
	v_mul_lo_u32 v209, v209, v210
	v_cndmask_b32_e64 v208, v206, 0, vcc
	v_add3_u32 v209, v208, v209, v211
	v_pk_mul_f32 v[200:201], v[200:201], v[204:205]
	v_pk_mul_f32 v[198:199], v[198:199], v[202:203]
	ds_write_b128 v209, v[198:201]
	s_waitcnt lgkmcnt(4)
	v_pk_fma_f32 v[220:221], v[10:11], v[158:159], 0 op_sel_hi:[1,1,0]
	v_pk_fma_f32 v[218:219], v[8:9], v[156:157], 0 op_sel_hi:[1,1,0]
	s_waitcnt lgkmcnt(3)
	v_pk_fma_f32 v[220:221], v[14:15], v[168:169], v[220:221]
	v_pk_fma_f32 v[218:219], v[12:13], v[166:167], v[218:219]
	s_waitcnt lgkmcnt(2)
	v_pk_fma_f32 v[220:221], v[150:151], v[172:173], v[220:221]
	v_pk_fma_f32 v[218:219], v[148:149], v[170:171], v[218:219]
	s_waitcnt lgkmcnt(1)
	v_pk_fma_f32 v[220:221], v[154:155], v[176:177], v[220:221]
	v_pk_fma_f32 v[218:219], v[152:153], v[174:175], v[218:219]
	v_mov_b32_e32 v208, v16
	v_mov_b32_e32 v209, v5
	v_mov_b32_e32 v210, v179
	v_mov_b32_e32 v211, v59
	v_mov_b32_e32 v212, v178
	v_add_u32_e32 v2, 0x2000, v2
	v_mul_hi_i32 v5, v4, s61
	v_lshrrev_b32_e32 v10, 31, v5
	v_ashrrev_i32_e32 v5, 3, v5
	v_and_b32_e32 v8, 60, v3
	v_add_u32_e32 v3, 0x800, v3
	v_add_u32_e32 v5, v5, v10
	s_movk_i32 s44, 0xffd0
	v_add_u32_e32 v9, 0x200, v4
	v_mad_u64_u32 v[16:17], s[44:45], v5, s44, v[4:5]
	v_mad_u64_u32 v[152:153], s[44:45], v5, s40, v[2:3]
	v_lshlrev_b32_e32 v59, 2, v8
	v_lshl_add_u32 v17, v5, 4, v2
	v_mov_b32_e32 v4, v9
	ds_read_b128 v[8:11], v152
	ds_read_b128 v[12:15], v152 offset:768
	v_add_u32_e32 v156, 0xfffeabd0, v17
	v_cmp_gt_u32_e32 vcc, 32, v16
	v_mov_b32_e32 v157, 0x210
	v_mov_b32_e32 v158, 0x110
	v_add_u32_e32 v160, 0xfffeaee0, v17
	v_add_u32_e32 v161, 0xfffeb1f0, v17
	ds_read_b128 v[148:151], v152 offset:1536
	ds_read_b128 v[152:155], v152 offset:2304
	v_add_u32_e32 v17, 0xfffeb500, v17
	v_cndmask_b32_e32 v179, v157, v158, vcc
	ds_read_b128 v[156:159], v156
	ds_read_b128 v[166:169], v160
	ds_read_b128 v[170:173], v161
	ds_read_b128 v[174:177], v17
	v_and_b32_e32 v178, -16, v16
	v_mul_f32_e32 v204, 0xbfb8aa3b, v220
	v_mul_f32_e32 v202, 0xbfb8aa3b, v218
	v_mul_f32_e32 v203, 0xbfb8aa3b, v219
	v_mul_f32_e32 v205, 0xbfb8aa3b, v221
	v_exp_f32_e32 v202, v202
	v_exp_f32_e32 v203, v203
	v_exp_f32_e32 v204, v204
	v_exp_f32_e32 v205, v205
	v_add_f32_e32 v202, 1.0, v202
	v_add_f32_e32 v203, 1.0, v203
	v_add_f32_e32 v204, 1.0, v204
	v_add_f32_e32 v205, 1.0, v205
	v_cmp_eq_u32_e32 vcc, 16, v212
	v_mov_b32_e32 v206, 0x15530
	v_mov_b32_e32 v207, 0x4400
	v_rcp_f32_e32 v202, v202
	v_rcp_f32_e32 v204, v204
	v_rcp_f32_e32 v205, v205
	v_rcp_f32_e32 v203, v203
	v_cndmask_b32_e32 v206, v206, v207, vcc
	v_add_u32_e32 v206, 0, v206
	v_cmp_gt_u32_e32 vcc, 16, v208
	v_mul_lo_u32 v209, v209, v210
	v_cndmask_b32_e64 v208, v206, 0, vcc
	v_add3_u32 v209, v208, v209, v211
	v_pk_mul_f32 v[220:221], v[220:221], v[204:205]
	v_pk_mul_f32 v[218:219], v[218:219], v[202:203]
	ds_write_b128 v209, v[218:221]
	s_waitcnt lgkmcnt(4)
	v_pk_fma_f32 v[200:201], v[10:11], v[158:159], 0 op_sel_hi:[1,1,0]
	v_pk_fma_f32 v[198:199], v[8:9], v[156:157], 0 op_sel_hi:[1,1,0]
	s_waitcnt lgkmcnt(3)
	v_pk_fma_f32 v[200:201], v[14:15], v[168:169], v[200:201]
	v_pk_fma_f32 v[198:199], v[12:13], v[166:167], v[198:199]
	s_waitcnt lgkmcnt(2)
	v_pk_fma_f32 v[200:201], v[150:151], v[172:173], v[200:201]
	v_pk_fma_f32 v[198:199], v[148:149], v[170:171], v[198:199]
	s_waitcnt lgkmcnt(1)
	v_pk_fma_f32 v[200:201], v[154:155], v[176:177], v[200:201]
	v_pk_fma_f32 v[198:199], v[152:153], v[174:175], v[198:199]
	v_mov_b32_e32 v208, v16
	v_mov_b32_e32 v209, v5
	v_mov_b32_e32 v210, v179
	v_mov_b32_e32 v211, v59
	v_mov_b32_e32 v212, v178
	v_add_u32_e32 v2, 0x2000, v2
	v_mul_hi_i32 v5, v4, s61
	v_lshrrev_b32_e32 v10, 31, v5
	v_ashrrev_i32_e32 v5, 3, v5
	v_and_b32_e32 v8, 60, v3
	v_add_u32_e32 v3, 0x800, v3
	v_add_u32_e32 v5, v5, v10
	s_movk_i32 s44, 0xffd0
	v_add_u32_e32 v9, 0x200, v4
	v_mad_u64_u32 v[16:17], s[44:45], v5, s44, v[4:5]
	v_mad_u64_u32 v[152:153], s[44:45], v5, s40, v[2:3]
	v_lshlrev_b32_e32 v59, 2, v8
	v_lshl_add_u32 v17, v5, 4, v2
	v_mov_b32_e32 v4, v9
	ds_read_b128 v[8:11], v152
	ds_read_b128 v[12:15], v152 offset:768
	v_add_u32_e32 v156, 0xfffeabd0, v17
	v_cmp_gt_u32_e32 vcc, 32, v16
	v_mov_b32_e32 v157, 0x210
	v_mov_b32_e32 v158, 0x110
	v_add_u32_e32 v160, 0xfffeaee0, v17
	v_add_u32_e32 v161, 0xfffeb1f0, v17
	ds_read_b128 v[148:151], v152 offset:1536
	ds_read_b128 v[152:155], v152 offset:2304
	v_add_u32_e32 v17, 0xfffeb500, v17
	v_cndmask_b32_e32 v179, v157, v158, vcc
	ds_read_b128 v[156:159], v156
	ds_read_b128 v[166:169], v160
	ds_read_b128 v[170:173], v161
	ds_read_b128 v[174:177], v17
	v_and_b32_e32 v178, -16, v16
	v_mul_f32_e32 v204, 0xbfb8aa3b, v200
	v_mul_f32_e32 v202, 0xbfb8aa3b, v198
	v_mul_f32_e32 v203, 0xbfb8aa3b, v199
	v_mul_f32_e32 v205, 0xbfb8aa3b, v201
	v_exp_f32_e32 v202, v202
	v_exp_f32_e32 v203, v203
	v_exp_f32_e32 v204, v204
	v_exp_f32_e32 v205, v205
	v_add_f32_e32 v202, 1.0, v202
	v_add_f32_e32 v203, 1.0, v203
	v_add_f32_e32 v204, 1.0, v204
	v_add_f32_e32 v205, 1.0, v205
	v_cmp_eq_u32_e32 vcc, 16, v212
	v_mov_b32_e32 v206, 0x15530
	v_mov_b32_e32 v207, 0x4400
	v_rcp_f32_e32 v202, v202
	v_rcp_f32_e32 v204, v204
	v_rcp_f32_e32 v205, v205
	v_rcp_f32_e32 v203, v203
	v_cndmask_b32_e32 v206, v206, v207, vcc
	v_add_u32_e32 v206, 0, v206
	v_cmp_gt_u32_e32 vcc, 16, v208
	v_mul_lo_u32 v209, v209, v210
	v_cndmask_b32_e64 v208, v206, 0, vcc
	v_add3_u32 v209, v208, v209, v211
	v_pk_mul_f32 v[200:201], v[200:201], v[204:205]
	v_pk_mul_f32 v[198:199], v[198:199], v[202:203]
	ds_write_b128 v209, v[198:201]
	s_waitcnt lgkmcnt(4)
	v_pk_fma_f32 v[220:221], v[10:11], v[158:159], 0 op_sel_hi:[1,1,0]
	v_pk_fma_f32 v[218:219], v[8:9], v[156:157], 0 op_sel_hi:[1,1,0]
	s_waitcnt lgkmcnt(3)
	v_pk_fma_f32 v[220:221], v[14:15], v[168:169], v[220:221]
	v_pk_fma_f32 v[218:219], v[12:13], v[166:167], v[218:219]
	s_waitcnt lgkmcnt(2)
	v_pk_fma_f32 v[220:221], v[150:151], v[172:173], v[220:221]
	v_pk_fma_f32 v[218:219], v[148:149], v[170:171], v[218:219]
	s_waitcnt lgkmcnt(1)
	v_pk_fma_f32 v[220:221], v[154:155], v[176:177], v[220:221]
	v_pk_fma_f32 v[218:219], v[152:153], v[174:175], v[218:219]
	v_mov_b32_e32 v208, v16
	v_mov_b32_e32 v209, v5
	v_mov_b32_e32 v210, v179
	v_mov_b32_e32 v211, v59
	v_mov_b32_e32 v212, v178
	v_add_u32_e32 v2, 0x2000, v2
	v_mul_hi_i32 v5, v4, s61
	v_lshrrev_b32_e32 v10, 31, v5
	v_ashrrev_i32_e32 v5, 3, v5
	v_and_b32_e32 v8, 60, v3
	v_add_u32_e32 v3, 0x800, v3
	v_add_u32_e32 v5, v5, v10
	s_movk_i32 s44, 0xffd0
	v_add_u32_e32 v9, 0x200, v4
	v_mad_u64_u32 v[16:17], s[44:45], v5, s44, v[4:5]
	v_mad_u64_u32 v[152:153], s[44:45], v5, s40, v[2:3]
	v_lshlrev_b32_e32 v59, 2, v8
	v_lshl_add_u32 v17, v5, 4, v2
	v_mov_b32_e32 v4, v9
	ds_read_b128 v[8:11], v152
	ds_read_b128 v[12:15], v152 offset:768
	v_add_u32_e32 v156, 0xfffeabd0, v17
	v_cmp_gt_u32_e32 vcc, 32, v16
	v_mov_b32_e32 v157, 0x210
	v_mov_b32_e32 v158, 0x110
	v_add_u32_e32 v160, 0xfffeaee0, v17
	v_add_u32_e32 v161, 0xfffeb1f0, v17
	ds_read_b128 v[148:151], v152 offset:1536
	ds_read_b128 v[152:155], v152 offset:2304
	v_add_u32_e32 v17, 0xfffeb500, v17
	v_cndmask_b32_e32 v179, v157, v158, vcc
	ds_read_b128 v[156:159], v156
	ds_read_b128 v[166:169], v160
	ds_read_b128 v[170:173], v161
	ds_read_b128 v[174:177], v17
	v_and_b32_e32 v178, -16, v16
	v_mul_f32_e32 v204, 0xbfb8aa3b, v220
	v_mul_f32_e32 v202, 0xbfb8aa3b, v218
	v_mul_f32_e32 v203, 0xbfb8aa3b, v219
	v_mul_f32_e32 v205, 0xbfb8aa3b, v221
	v_exp_f32_e32 v202, v202
	v_exp_f32_e32 v203, v203
	v_exp_f32_e32 v204, v204
	v_exp_f32_e32 v205, v205
	v_add_f32_e32 v202, 1.0, v202
	v_add_f32_e32 v203, 1.0, v203
	v_add_f32_e32 v204, 1.0, v204
	v_add_f32_e32 v205, 1.0, v205
	v_cmp_eq_u32_e32 vcc, 16, v212
	v_mov_b32_e32 v206, 0x15530
	v_mov_b32_e32 v207, 0x4400
	v_rcp_f32_e32 v202, v202
	v_rcp_f32_e32 v204, v204
	v_rcp_f32_e32 v205, v205
	v_rcp_f32_e32 v203, v203
	v_cndmask_b32_e32 v206, v206, v207, vcc
	v_add_u32_e32 v206, 0, v206
	v_cmp_gt_u32_e32 vcc, 16, v208
	v_mul_lo_u32 v209, v209, v210
	v_cndmask_b32_e64 v208, v206, 0, vcc
	v_add3_u32 v209, v208, v209, v211
	v_pk_mul_f32 v[220:221], v[220:221], v[204:205]
	v_pk_mul_f32 v[218:219], v[218:219], v[202:203]
	ds_write_b128 v209, v[218:221]
	s_waitcnt lgkmcnt(4)
	v_pk_fma_f32 v[200:201], v[10:11], v[158:159], 0 op_sel_hi:[1,1,0]
	v_pk_fma_f32 v[198:199], v[8:9], v[156:157], 0 op_sel_hi:[1,1,0]
	s_waitcnt lgkmcnt(3)
	v_pk_fma_f32 v[200:201], v[14:15], v[168:169], v[200:201]
	v_pk_fma_f32 v[198:199], v[12:13], v[166:167], v[198:199]
	s_waitcnt lgkmcnt(2)
	v_pk_fma_f32 v[200:201], v[150:151], v[172:173], v[200:201]
	v_pk_fma_f32 v[198:199], v[148:149], v[170:171], v[198:199]
	s_waitcnt lgkmcnt(1)
	v_pk_fma_f32 v[200:201], v[154:155], v[176:177], v[200:201]
	v_pk_fma_f32 v[198:199], v[152:153], v[174:175], v[198:199]
	v_mov_b32_e32 v208, v16
	v_mov_b32_e32 v209, v5
	v_mov_b32_e32 v210, v179
	v_mov_b32_e32 v211, v59
	v_mov_b32_e32 v212, v178
	v_add_u32_e32 v2, 0x2000, v2
	v_mul_hi_i32 v5, v4, s61
	v_lshrrev_b32_e32 v10, 31, v5
	v_ashrrev_i32_e32 v5, 3, v5
	v_and_b32_e32 v8, 60, v3
	v_add_u32_e32 v3, 0x800, v3
	v_add_u32_e32 v5, v5, v10
	s_movk_i32 s44, 0xffd0
	v_add_u32_e32 v9, 0x200, v4
	v_mad_u64_u32 v[16:17], s[44:45], v5, s44, v[4:5]
	v_mad_u64_u32 v[152:153], s[44:45], v5, s40, v[2:3]
	v_lshlrev_b32_e32 v59, 2, v8
	v_lshl_add_u32 v17, v5, 4, v2
	v_mov_b32_e32 v4, v9
	ds_read_b128 v[8:11], v152
	ds_read_b128 v[12:15], v152 offset:768
	v_add_u32_e32 v156, 0xfffeabd0, v17
	v_cmp_gt_u32_e32 vcc, 32, v16
	v_mov_b32_e32 v157, 0x210
	v_mov_b32_e32 v158, 0x110
	v_add_u32_e32 v160, 0xfffeaee0, v17
	v_add_u32_e32 v161, 0xfffeb1f0, v17
	ds_read_b128 v[148:151], v152 offset:1536
	ds_read_b128 v[152:155], v152 offset:2304
	v_add_u32_e32 v17, 0xfffeb500, v17
	v_cndmask_b32_e32 v179, v157, v158, vcc
	ds_read_b128 v[156:159], v156
	ds_read_b128 v[166:169], v160
	ds_read_b128 v[170:173], v161
	ds_read_b128 v[174:177], v17
	v_and_b32_e32 v178, -16, v16
	v_mul_f32_e32 v204, 0xbfb8aa3b, v200
	v_mul_f32_e32 v202, 0xbfb8aa3b, v198
	v_mul_f32_e32 v203, 0xbfb8aa3b, v199
	v_mul_f32_e32 v205, 0xbfb8aa3b, v201
	v_exp_f32_e32 v202, v202
	v_exp_f32_e32 v203, v203
	v_exp_f32_e32 v204, v204
	v_exp_f32_e32 v205, v205
	v_add_f32_e32 v202, 1.0, v202
	v_add_f32_e32 v203, 1.0, v203
	v_add_f32_e32 v204, 1.0, v204
	v_add_f32_e32 v205, 1.0, v205
	v_cmp_eq_u32_e32 vcc, 16, v212
	v_mov_b32_e32 v206, 0x15530
	v_mov_b32_e32 v207, 0x4400
	v_rcp_f32_e32 v202, v202
	v_rcp_f32_e32 v204, v204
	v_rcp_f32_e32 v205, v205
	v_rcp_f32_e32 v203, v203
	v_cndmask_b32_e32 v206, v206, v207, vcc
	v_add_u32_e32 v206, 0, v206
	v_cmp_gt_u32_e32 vcc, 16, v208
	v_mul_lo_u32 v209, v209, v210
	v_cndmask_b32_e64 v208, v206, 0, vcc
	v_add3_u32 v209, v208, v209, v211
	v_pk_mul_f32 v[200:201], v[200:201], v[204:205]
	v_pk_mul_f32 v[198:199], v[198:199], v[202:203]
	ds_write_b128 v209, v[198:201]
	s_waitcnt lgkmcnt(4)
	v_pk_fma_f32 v[220:221], v[10:11], v[158:159], 0 op_sel_hi:[1,1,0]
	v_pk_fma_f32 v[218:219], v[8:9], v[156:157], 0 op_sel_hi:[1,1,0]
	s_waitcnt lgkmcnt(3)
	v_pk_fma_f32 v[220:221], v[14:15], v[168:169], v[220:221]
	v_pk_fma_f32 v[218:219], v[12:13], v[166:167], v[218:219]
	s_waitcnt lgkmcnt(2)
	v_pk_fma_f32 v[220:221], v[150:151], v[172:173], v[220:221]
	v_pk_fma_f32 v[218:219], v[148:149], v[170:171], v[218:219]
	s_waitcnt lgkmcnt(1)
	v_pk_fma_f32 v[220:221], v[154:155], v[176:177], v[220:221]
	v_pk_fma_f32 v[218:219], v[152:153], v[174:175], v[218:219]
	v_mov_b32_e32 v208, v16
	v_mov_b32_e32 v209, v5
	v_mov_b32_e32 v210, v179
	v_mov_b32_e32 v211, v59
	v_mov_b32_e32 v212, v178
	v_mul_f32_e32 v204, 0xbfb8aa3b, v220
	v_mul_f32_e32 v202, 0xbfb8aa3b, v218
	v_mul_f32_e32 v203, 0xbfb8aa3b, v219
	v_mul_f32_e32 v205, 0xbfb8aa3b, v221
	v_exp_f32_e32 v202, v202
	v_exp_f32_e32 v203, v203
	v_exp_f32_e32 v204, v204
	v_exp_f32_e32 v205, v205
	v_add_f32_e32 v202, 1.0, v202
	v_add_f32_e32 v203, 1.0, v203
	v_add_f32_e32 v204, 1.0, v204
	v_add_f32_e32 v205, 1.0, v205
	v_cmp_eq_u32_e32 vcc, 16, v212
	v_mov_b32_e32 v206, 0x15530
	v_mov_b32_e32 v207, 0x4400
	v_rcp_f32_e32 v202, v202
	v_rcp_f32_e32 v204, v204
	v_rcp_f32_e32 v205, v205
	v_rcp_f32_e32 v203, v203
	v_cndmask_b32_e32 v206, v206, v207, vcc
	v_add_u32_e32 v206, 0, v206
	v_cmp_gt_u32_e32 vcc, 16, v208
	v_mul_lo_u32 v209, v209, v210
	v_cndmask_b32_e64 v208, v206, 0, vcc
	v_add3_u32 v209, v208, v209, v211
	v_pk_mul_f32 v[220:221], v[220:221], v[204:205]
	v_pk_mul_f32 v[218:219], v[218:219], v[202:203]
	ds_write_b128 v209, v[218:221]
